# compressed-attention pass 2 loop body rescheduled by hand: K fragments, 16 bias-LUT gathers and V^T fragments all issued ahead of use (was one LDS round trip per element)
# speedup vs baseline: 1.0100x; 1.0036x over previous
; #define MFMA32(a, b, c) __builtin_amdgcn_mfma_f32_32x32x16_bf16((a), (b), (c), 0, 0, 0)
; DI int crow(int i, int hh) { return (i & 3) + 8 * (i >> 2) + 4 * hh; }
; DI void attn_item(const Params& P, int item, unsigned char* smem) {
;     ...
;         for (int kt = 0; kt < 4; ++kt) {
;             f32x16 sc;
; #pragma unroll
;             for (int i = 0; i < 16; ++i) sc[i] = 0.f;
; #pragma unroll
;             for (int kk = 0; kk < 8; ++kk) { const bf16x8 a = *(const bf16x8*)(kl + kt * (32 * 272) + 32 * kk); sc = MFMA32(a, qf[kk], sc); }
; #pragma unroll
;             for (int i = 0; i < 16; ++i) { const int c = 32 * kt + crow(i, hh), dist = tq - (16 * c + 31);
;                 const int di = dist < 0 ? 0 : (dist > 255 ? 255 : dist);
;                 const float v = sc[i] * QK_C1 + lutH[di];
;                 sc[i] = __builtin_amdgcn_exp2f(((dist >= 0 && c < 127) ? v : NEGF) - fmaxf(mx, -1e29f)) * inv; }
.LBB0_760:
	ds_read_b128 v[208:211], v107
	ds_read_b128 v[212:215], v107 offset:32
	ds_read_b128 v[216:219], v107 offset:64
	ds_read_b128 v[220:223], v107 offset:96
	ds_read_b128 v[224:227], v107 offset:128
	ds_read_b128 v[228:231], v107 offset:160
	ds_read_b128 v[232:235], v107 offset:192
	ds_read_b128 v[236:239], v107 offset:224
	v_cmp_gt_u32_e64 s[0:1], s36, v2
	v_add_u32_e32 v190, s2, v104
	s_addk_i32 s2, 0xfe00
	v_add_u32_e32 v2, 32, v2
	v_add_u32_e32 v107, 0x2200, v107
	v_add_u32_e32 v146, 0x7a1, v190
	v_med3_i32 v174, v146, 0, v194
	v_lshl_add_u32 v174, v174, 2, v202
	ds_read_b32 v174, v174
	v_add_u32_e32 v147, 0x791, v190
	v_med3_i32 v175, v147, 0, v194
	v_lshl_add_u32 v175, v175, 2, v202
	ds_read_b32 v175, v175
	s_waitcnt lgkmcnt(9)
	v_mfma_f32_32x32x16_bf16 v[68:83], v[208:211], v[114:117], 0
	v_add_u32_e32 v148, 0x781, v190
	v_med3_i32 v176, v148, 0, v194
	v_lshl_add_u32 v176, v176, 2, v202
	ds_read_b32 v176, v176
	v_add_u32_e32 v149, 0x771, v190
	v_med3_i32 v177, v149, 0, v194
	v_lshl_add_u32 v177, v177, 2, v202
	ds_read_b32 v177, v177
	s_waitcnt lgkmcnt(10)
	v_mfma_f32_32x32x16_bf16 v[68:83], v[212:215], v[118:121], v[68:83]
	v_add_u32_e32 v150, 0x721, v190
	v_med3_i32 v178, v150, 0, v194
	v_lshl_add_u32 v178, v178, 2, v202
	ds_read_b32 v178, v178
	v_add_u32_e32 v151, 0x711, v190
	v_med3_i32 v179, v151, 0, v194
	v_lshl_add_u32 v179, v179, 2, v202
	ds_read_b32 v179, v179
	s_waitcnt lgkmcnt(11)
	v_mfma_f32_32x32x16_bf16 v[68:83], v[216:219], v[122:125], v[68:83]
	v_add_u32_e32 v152, 0x701, v190
	v_med3_i32 v180, v152, 0, v194
	v_lshl_add_u32 v180, v180, 2, v202
	ds_read_b32 v180, v180
	v_add_u32_e32 v153, 0x6f1, v190
	v_med3_i32 v181, v153, 0, v194
	v_lshl_add_u32 v181, v181, 2, v202
	ds_read_b32 v181, v181
	s_waitcnt lgkmcnt(12)
	v_mfma_f32_32x32x16_bf16 v[68:83], v[220:223], v[126:129], v[68:83]
	v_add_u32_e32 v154, 0x6a1, v190
	v_med3_i32 v182, v154, 0, v194
	v_lshl_add_u32 v182, v182, 2, v202
	ds_read_b32 v182, v182
	v_add_u32_e32 v155, 0x691, v190
	v_med3_i32 v183, v155, 0, v194
	v_lshl_add_u32 v183, v183, 2, v202
	ds_read_b32 v183, v183
	s_waitcnt lgkmcnt(13)
	v_mfma_f32_32x32x16_bf16 v[68:83], v[224:227], v[130:133], v[68:83]
	v_add_u32_e32 v156, 0x681, v190
	v_med3_i32 v184, v156, 0, v194
	v_lshl_add_u32 v184, v184, 2, v202
	ds_read_b32 v184, v184
	v_add_u32_e32 v157, 0x671, v190
	v_med3_i32 v185, v157, 0, v194
	v_lshl_add_u32 v185, v185, 2, v202
	ds_read_b32 v185, v185
	s_waitcnt lgkmcnt(13)
	v_mfma_f32_32x32x16_bf16 v[68:83], v[228:231], v[134:137], v[68:83]
	v_add_u32_e32 v158, 0x621, v190
	v_med3_i32 v186, v158, 0, v194
	v_lshl_add_u32 v186, v186, 2, v202
	ds_read_b32 v186, v186
	v_add_u32_e32 v159, 0x611, v190
	v_med3_i32 v187, v159, 0, v194
	v_lshl_add_u32 v187, v187, 2, v202
	ds_read_b32 v187, v187
	s_waitcnt lgkmcnt(13)
	v_mfma_f32_32x32x16_bf16 v[68:83], v[232:235], v[138:141], v[68:83]
	v_add_u32_e32 v160, 0x601, v190
	v_med3_i32 v188, v160, 0, v194
	v_lshl_add_u32 v188, v188, 2, v202
	ds_read_b32 v188, v188
	v_add_u32_e32 v161, 0x5f1, v190
	v_med3_i32 v189, v161, 0, v194
	v_lshl_add_u32 v189, v189, 2, v202
	ds_read_b32 v189, v189
	s_waitcnt lgkmcnt(13)
	v_mfma_f32_32x32x16_bf16 v[68:83], v[236:239], v[142:145], v[68:83]
	v_add_u32_e32 v191, 0x2000, v106
	v_add_u32_e32 v192, 0x4000, v106
	v_add_u32_e32 v193, 0x6000, v106
	s_waitcnt lgkmcnt(7)
	ds_read2_b64 v[208:211], v106 offset1:2
	ds_read2_b64 v[212:215], v191 offset0:64 offset1:66
	ds_read2_b64 v[216:219], v106 offset0:4 offset1:6
	ds_read2_b64 v[220:223], v191 offset0:68 offset1:70
	ds_read2_b64 v[224:227], v192 offset0:128 offset1:130
	ds_read2_b64 v[228:231], v192 offset0:132 offset1:134
	ds_read2_b64 v[232:235], v193 offset0:192 offset1:194
	ds_read2_b64 v[236:239], v193 offset0:196 offset1:198
	v_add_u32_e32 v106, 64, v106
	v_add_u32_e32 v112, 0x11000, v96
	v_add_u32_e32 v96, 32, v96
	s_waitcnt lgkmcnt(15)
	v_cmp_lt_i32_e32 vcc, -1, v146
	v_fmac_f32_e32 v174, 0x3e0293ee, v68
	s_nop 0
	v_cndmask_b32_e32 v68, v195, v174, vcc
	s_waitcnt lgkmcnt(15)
	v_cmp_lt_i32_e32 vcc, -1, v147
	v_fmac_f32_e32 v175, 0x3e0293ee, v69
	v_sub_f32_e32 v68, v68, v105
	v_cndmask_b32_e32 v69, v195, v175, vcc
	v_exp_f32_e32 v68, v68
	s_waitcnt lgkmcnt(15)
	v_cmp_lt_i32_e32 vcc, -1, v148
	v_fmac_f32_e32 v176, 0x3e0293ee, v70
	v_sub_f32_e32 v69, v69, v105
	v_cndmask_b32_e32 v70, v195, v176, vcc
	v_exp_f32_e32 v69, v69
	s_waitcnt lgkmcnt(15)
	v_cmp_lt_i32_e32 vcc, -1, v149
	v_fmac_f32_e32 v177, 0x3e0293ee, v71
	v_sub_f32_e32 v70, v70, v105
	v_cndmask_b32_e32 v71, v195, v177, vcc
	v_exp_f32_e32 v70, v70
	v_pk_mul_f32 v[68:69], v[94:95], v[68:69]
	s_waitcnt lgkmcnt(15)
; #define MFMA32(a, b, c) __builtin_amdgcn_mfma_f32_32x32x16_bf16((a), (b), (c), 0, 0, 0)
; DI bf16x8 packp(const f32x16& x, int s) { u32x4 p; p.x = pk2(x[8 * s], x[8 * s + 1]); p.y = pk2(x[8 * s + 2], x[8 * s + 3]); p.z = pk2(x[8 * s + 4], x[8 * s + 5]); p.w = pk2(x[8 * s + 6], x[8 * s + 7]); return __builtin_bit_cast(bf16x8, p); }
; DI int crow(int i, int hh) { return (i & 3) + 8 * (i >> 2) + 4 * hh; }
; DI bf16x8 lds2x4(const unsigned char* p) { const s16x4 a = *(const s16x4*)p, b = *(const s16x4*)(p + 16); return __builtin_shufflevector(a, b, 0, 1, 2, 3, 4, 5, 6, 7); }
; DI void attn_item(const Params& P, int item, unsigned char* smem) {
;     ...
;             for (int i = 0; i < 16; ++i) { const int c = 32 * kt + crow(i, hh), dist = tq - (16 * c + 31);
;                 const int di = dist < 0 ? 0 : (dist > 255 ? 255 : dist);
;                 const float v = sc[i] * QK_C1 + lutH[di];
;                 sc[i] = __builtin_amdgcn_exp2f(((dist >= 0 && c < 127) ? v : NEGF) - fmaxf(mx, -1e29f)) * inv; }
; #pragma unroll
;             for (int gi = 0; gi < 4; ++gi) { const int jb = 8 * kt + 2 * gi + hh; const float p3 = 0.5f * sc[4 * gi + 3];
;                 impM[(hg * 64 + qloc) * 33 + jb] = sc[4 * gi] + sc[4 * gi + 1] + sc[4 * gi + 2] + p3;
;                 impS[(hg * 64 + qloc) * 33 + jb] = p3; }
; #pragma unroll
;             for (int s2 = 0; s2 < 2; ++s2) { const bf16x8 pb = packp(sc, s2);
; #pragma unroll
;                 for (int dt = 0; dt < 4; ++dt) { const bf16x8 a = lds2x4(vl + dt * (32 * 272) + 64 * kt + 32 * s2); oc[dt] = MFMA32(a, pb, oc[dt]); } }
	v_cmp_lt_i32_e32 vcc, -1, v150
	v_fmac_f32_e32 v178, 0x3e0293ee, v72
	v_sub_f32_e32 v71, v71, v105
	v_cndmask_b32_e32 v72, v195, v178, vcc
	v_exp_f32_e32 v71, v71
	s_waitcnt lgkmcnt(15)
	v_cmp_lt_i32_e32 vcc, -1, v151
	v_fmac_f32_e32 v179, 0x3e0293ee, v73
	v_sub_f32_e32 v72, v72, v105
	v_cndmask_b32_e32 v73, v195, v179, vcc
	v_exp_f32_e32 v72, v72
	v_pk_mul_f32 v[70:71], v[94:95], v[70:71]
	s_waitcnt lgkmcnt(15)
	v_cmp_lt_i32_e32 vcc, -1, v152
	v_fmac_f32_e32 v180, 0x3e0293ee, v74
	v_sub_f32_e32 v73, v73, v105
	v_cndmask_b32_e32 v74, v195, v180, vcc
	v_exp_f32_e32 v73, v73
	s_waitcnt lgkmcnt(15)
	v_cmp_lt_i32_e32 vcc, -1, v153
	v_fmac_f32_e32 v181, 0x3e0293ee, v75
	v_sub_f32_e32 v74, v74, v105
	v_cndmask_b32_e32 v75, v195, v181, vcc
	v_exp_f32_e32 v74, v74
	v_pk_mul_f32 v[72:73], v[94:95], v[72:73]
	s_waitcnt lgkmcnt(15)
	v_cmp_lt_i32_e32 vcc, -1, v154
	v_fmac_f32_e32 v182, 0x3e0293ee, v76
	v_sub_f32_e32 v75, v75, v105
	v_cndmask_b32_e32 v76, v195, v182, vcc
	v_exp_f32_e32 v75, v75
	s_waitcnt lgkmcnt(14)
	v_cmp_lt_i32_e32 vcc, -1, v155
	v_fmac_f32_e32 v183, 0x3e0293ee, v77
	v_sub_f32_e32 v76, v76, v105
	v_cndmask_b32_e32 v77, v195, v183, vcc
	v_exp_f32_e32 v76, v76
	v_pk_mul_f32 v[74:75], v[94:95], v[74:75]
	s_waitcnt lgkmcnt(13)
	v_cmp_lt_i32_e32 vcc, -1, v156
	v_fmac_f32_e32 v184, 0x3e0293ee, v78
	v_sub_f32_e32 v77, v77, v105
	v_cndmask_b32_e32 v78, v195, v184, vcc
	v_exp_f32_e32 v77, v77
	s_waitcnt lgkmcnt(12)
	v_cmp_lt_i32_e32 vcc, -1, v157
	v_fmac_f32_e32 v185, 0x3e0293ee, v79
	v_sub_f32_e32 v78, v78, v105
	v_cndmask_b32_e32 v79, v195, v185, vcc
	v_exp_f32_e32 v78, v78
	v_pk_mul_f32 v[76:77], v[94:95], v[76:77]
	s_waitcnt lgkmcnt(11)
	v_cmp_lt_i32_e32 vcc, -1, v158
	v_fmac_f32_e32 v186, 0x3e0293ee, v80
	v_sub_f32_e32 v79, v79, v105
	v_cndmask_b32_e32 v80, v195, v186, vcc
	v_exp_f32_e32 v79, v79
	s_waitcnt lgkmcnt(10)
	v_cmp_lt_i32_e32 vcc, -1, v159
	v_fmac_f32_e32 v187, 0x3e0293ee, v81
	v_sub_f32_e32 v80, v80, v105
	v_cndmask_b32_e32 v81, v195, v187, vcc
	v_exp_f32_e32 v80, v80
	v_pk_mul_f32 v[78:79], v[94:95], v[78:79]
	s_waitcnt lgkmcnt(9)
	v_cmp_lt_i32_e32 vcc, -1, v160
	v_fmac_f32_e32 v188, 0x3e0293ee, v82
	v_sub_f32_e32 v81, v81, v105
	v_cndmask_b32_e32 v82, v195, v188, vcc
	v_exp_f32_e32 v81, v81
	s_waitcnt lgkmcnt(8)
	v_cmp_lt_i32_e32 vcc, -1, v161
	v_fmac_f32_e32 v189, 0x3e0293ee, v83
	v_sub_f32_e32 v82, v82, v105
	s_and_b64 vcc, s[0:1], vcc
	s_nop 1
	v_cndmask_b32_e32 v83, v195, v189, vcc
	v_exp_f32_e32 v82, v82
	v_pk_mul_f32 v[80:81], v[94:95], v[80:81]
	v_sub_f32_e32 v83, v83, v105
	v_exp_f32_e32 v83, v83
	v_cvt_pk_bf16_f32 v108, v68, v69
	v_pk_mul_f32 v[82:83], v[94:95], v[82:83]
	v_cvt_pk_bf16_f32 v109, v70, v71
	v_cvt_pk_bf16_f32 v110, v72, v73
	v_cvt_pk_bf16_f32 v111, v74, v75
	v_add_f32_e32 v97, v68, v69
	v_add_f32_e32 v97, v70, v97
	v_fmac_f32_e32 v97, 0.5, v71
	v_mul_f32_e32 v98, 0.5, v71
	ds_write_b32 v112, v97
	ds_write_b32 v112, v98 offset:33792
	v_add_f32_e32 v99, v72, v73
	v_add_f32_e32 v99, v74, v99
	v_fmac_f32_e32 v99, 0.5, v75
	v_mul_f32_e32 v100, 0.5, v75
	ds_write_b32 v112, v99 offset:8
	ds_write_b32 v112, v100 offset:33800
	s_waitcnt lgkmcnt(11)
	v_mfma_f32_32x32x16_bf16 v[52:67], v[208:211], v[108:111], v[52:67]
	s_waitcnt lgkmcnt(10)
	v_mfma_f32_32x32x16_bf16 v[36:51], v[212:215], v[108:111], v[36:51]
	v_cvt_pk_bf16_f32 v72, v76, v77
	v_cvt_pk_bf16_f32 v73, v78, v79
	v_cvt_pk_bf16_f32 v74, v80, v81
	v_cvt_pk_bf16_f32 v75, v82, v83
	v_add_f32_e32 v97, v76, v77
	v_add_f32_e32 v97, v78, v97
	v_fmac_f32_e32 v97, 0.5, v79
	v_mul_f32_e32 v98, 0.5, v79
	ds_write_b32 v112, v97 offset:16
	ds_write_b32 v112, v98 offset:33808
	v_add_f32_e32 v99, v80, v81
	v_add_f32_e32 v99, v82, v99
	v_fmac_f32_e32 v99, 0.5, v83
	v_mul_f32_e32 v100, 0.5, v83
	ds_write_b32 v112, v99 offset:24
	ds_write_b32 v112, v100 offset:33816
	s_cmpk_lg_i32 s2, 0xf800
	s_waitcnt lgkmcnt(13)
	v_mfma_f32_32x32x16_bf16 v[52:67], v[216:219], v[72:75], v[52:67]
	s_waitcnt lgkmcnt(12)
	v_mfma_f32_32x32x16_bf16 v[36:51], v[220:223], v[72:75], v[36:51]
	s_waitcnt lgkmcnt(11)
	v_mfma_f32_32x32x16_bf16 v[20:35], v[224:227], v[108:111], v[20:35]
	s_waitcnt lgkmcnt(10)
	v_mfma_f32_32x32x16_bf16 v[20:35], v[228:231], v[72:75], v[20:35]
	s_waitcnt lgkmcnt(9)
	v_mfma_f32_32x32x16_bf16 v[4:19], v[232:235], v[108:111], v[4:19]
	s_waitcnt lgkmcnt(0)
	v_mfma_f32_32x32x16_bf16 v[4:19], v[236:239], v[72:75], v[4:19]
	s_cbranch_scc1 .LBB0_760
	v_readlane_b32 s0, v244, 9
	s_mov_b32 s2, 0
	v_cmp_eq_u32_e32 vcc, 0, v84
	v_cmp_ne_u32_e64 s[6:7], 0, v84
	v_or_b32_e32 v2, 0x840, v84
	v_or_b32_e32 v68, 0x1080, v84
	v_or_b32_e32 v69, 0x18c0, v84
	v_lshl_add_u32 v70, v90, 2, s0
	v_mov_b32_e32 v71, v90
	s_barrier
	s_branch .LBB0_763
